# XB seams: acquire invalidate issued before polling (followers) / right after top arrival (XCD leader) instead of after release
# speedup vs baseline: 1.0303x; 1.0134x over previous
.LBB0_119:
	s_or_b64 exec, exec, s[16:17]
	s_waitcnt vmcnt(0)
	v_readfirstlane_b32 s14, v3
	s_waitcnt lgkmcnt(0)
	v_mul_lo_u32 v1, v1, v144
	v_add3_u32 v2, s14, v2, 1
	v_cmp_ne_u32_e32 vcc, v2, v1
	s_and_saveexec_b64 s[14:15], vcc
	s_xor_b64 s[14:15], exec, s[14:15]
	s_cbranch_execz .LBB0_124
	s_lshl_b64 s[16:17], s[40:41], 2
	s_add_u32 s16, s12, s16
	s_addc_u32 s17, s13, s17
	v_mov_b32_e32 v0, 0xdd000
	buffer_inv sc1
	global_load_dword v0, v0, s[16:17] offset:1024 sc1
	s_add_u32 s16, s16, 0xdd400
	s_addc_u32 s17, s17, 0
	s_waitcnt vmcnt(0)
	v_cmp_eq_u32_e32 vcc, v0, v97
	s_and_saveexec_b64 s[18:19], vcc
	s_cbranch_execz .LBB0_123
	s_mov_b64 s[20:21], 0
.LBB0_122:
	s_sleep 0
	global_load_dword v0, v179, s[16:17] sc1
	s_waitcnt vmcnt(0)
	v_cmp_ne_u32_e32 vcc, v0, v97
	s_or_b64 s[20:21], vcc, s[20:21]
	s_andn2_b64 exec, exec, s[20:21]
	s_cbranch_execnz .LBB0_122
.LBB0_123:
	s_or_b64 exec, exec, s[18:19]
	s_waitcnt vmcnt(0)
.LBB0_124:
	s_andn2_saveexec_b64 s[14:15], s[14:15]
	s_cbranch_execz .LBB0_139
	s_mov_b64 s[16:17], exec
	buffer_wbl2 sc1
	s_waitcnt vmcnt(0)
	v_mbcnt_lo_u32_b32 v1, s16, 0
	v_mbcnt_hi_u32_b32 v1, s17, v1
	v_cmp_eq_u32_e32 vcc, 0, v1
	s_and_saveexec_b64 s[18:19], vcc
	s_cbranch_execz .LBB0_127
	s_bcnt1_i32_b64 s16, s[16:17]
	v_mov_b32_e32 v2, s16
	v_mov_b32_e32 v3, 0xde000
	global_atomic_add v2, v3, v2, s[12:13] offset:1024 sc0
.LBB0_127:
	s_or_b64 exec, exec, s[18:19]
	s_waitcnt vmcnt(0)
	buffer_inv sc1
	v_readfirstlane_b32 s16, v2
	v_mul_lo_u32 v0, v0, v144
	s_nop 0
	v_add3_u32 v1, s16, v1, 1
	s_add_u32 s16, s12, 0xde500
	v_cmp_ne_u32_e32 vcc, v1, v0
	s_addc_u32 s17, s13, 0
	s_and_saveexec_b64 s[18:19], vcc
	s_xor_b64 s[18:19], exec, s[18:19]
	s_cbranch_execz .LBB0_132
	global_load_dword v0, v179, s[16:17] sc1
	s_waitcnt vmcnt(0)
	v_cmp_eq_u32_e32 vcc, v0, v97
	s_and_saveexec_b64 s[20:21], vcc
	s_cbranch_execz .LBB0_131
	s_mov_b64 s[22:23], 0

.LBB0_136:
	s_or_b64 exec, exec, s[18:19]
	s_mov_b64 s[16:17], exec
	v_mbcnt_lo_u32_b32 v0, s16, 0
	v_mbcnt_hi_u32_b32 v0, s17, v0
	v_cmp_eq_u32_e32 vcc, 0, v0
	s_waitcnt vmcnt(0)
	s_and_saveexec_b64 s[18:19], vcc
	s_cbranch_execz .LBB0_138
	s_lshl_b64 s[20:21], s[40:41], 2
	s_add_u32 s12, s12, s20
	s_addc_u32 s13, s13, s21
	s_bcnt1_i32_b64 s16, s[16:17]
	v_mov_b32_e32 v0, s16
	v_mov_b32_e32 v1, 0xdd000
	global_atomic_add v1, v0, s[12:13] offset:1024

.LBB0_183:
	s_or_b64 exec, exec, s[16:17]
	s_waitcnt vmcnt(0)
	v_readfirstlane_b32 s14, v3
	s_waitcnt lgkmcnt(0)
	v_mul_lo_u32 v1, v1, v116
	v_add3_u32 v2, s14, v2, 1
	v_cmp_ne_u32_e32 vcc, v2, v1
	s_and_saveexec_b64 s[14:15], vcc
	s_xor_b64 s[14:15], exec, s[14:15]
	s_cbranch_execz .LBB0_188
	s_lshl_b64 s[16:17], s[40:41], 2
	s_add_u32 s16, s12, s16
	s_addc_u32 s17, s13, s17
	v_mov_b32_e32 v0, 0xdd000
	buffer_inv sc1
	global_load_dword v0, v0, s[16:17] offset:1024 sc1
	s_add_u32 s16, s16, 0xdd400
	s_addc_u32 s17, s17, 0
	s_waitcnt vmcnt(0)
	v_cmp_eq_u32_e32 vcc, v0, v144
	s_and_saveexec_b64 s[18:19], vcc
	s_cbranch_execz .LBB0_187
	s_mov_b64 s[20:21], 0
.LBB0_186:
	s_sleep 0
	global_load_dword v0, v179, s[16:17] sc1
	s_waitcnt vmcnt(0)
	v_cmp_ne_u32_e32 vcc, v0, v144
	s_or_b64 s[20:21], vcc, s[20:21]
	s_andn2_b64 exec, exec, s[20:21]
	s_cbranch_execnz .LBB0_186
.LBB0_187:
	s_or_b64 exec, exec, s[18:19]
	s_waitcnt vmcnt(0)
.LBB0_188:
	s_andn2_saveexec_b64 s[14:15], s[14:15]
	s_cbranch_execz .LBB0_203
	s_mov_b64 s[16:17], exec
	buffer_wbl2 sc1
	s_waitcnt vmcnt(0)
	v_mbcnt_lo_u32_b32 v1, s16, 0
	v_mbcnt_hi_u32_b32 v1, s17, v1
	v_cmp_eq_u32_e32 vcc, 0, v1
	s_and_saveexec_b64 s[18:19], vcc
	s_cbranch_execz .LBB0_191
	s_bcnt1_i32_b64 s16, s[16:17]
	v_mov_b32_e32 v2, s16
	v_mov_b32_e32 v3, 0xde000
	global_atomic_add v2, v3, v2, s[12:13] offset:1024 sc0
.LBB0_191:
	s_or_b64 exec, exec, s[18:19]
	s_waitcnt vmcnt(0)
	buffer_inv sc1
	v_readfirstlane_b32 s16, v2
	v_mul_lo_u32 v0, v0, v116
	s_nop 0
	v_add3_u32 v1, s16, v1, 1
	s_add_u32 s16, s12, 0xde500
	v_cmp_ne_u32_e32 vcc, v1, v0
	s_addc_u32 s17, s13, 0
	s_and_saveexec_b64 s[18:19], vcc
	s_xor_b64 s[18:19], exec, s[18:19]
	s_cbranch_execz .LBB0_196
	global_load_dword v0, v179, s[16:17] sc1
	s_waitcnt vmcnt(0)
	v_cmp_eq_u32_e32 vcc, v0, v144
	s_and_saveexec_b64 s[20:21], vcc
	s_cbranch_execz .LBB0_195
	s_mov_b64 s[22:23], 0

.LBB0_1495:
	s_or_b64 exec, exec, s[16:17]
	s_waitcnt vmcnt(0)
	v_readfirstlane_b32 s14, v3
	s_waitcnt lgkmcnt(0)
	v_mul_lo_u32 v1, v1, v97
	v_add3_u32 v2, s14, v2, 1
	v_cmp_ne_u32_e32 vcc, v2, v1
	s_and_saveexec_b64 s[14:15], vcc
	s_xor_b64 s[14:15], exec, s[14:15]
	s_cbranch_execz .LBB0_1500
	s_lshl_b64 s[16:17], s[40:41], 2
	s_add_u32 s16, s12, s16
	s_addc_u32 s17, s13, s17
	v_mov_b32_e32 v0, 0xdd000
	buffer_inv sc1
	global_load_dword v0, v0, s[16:17] offset:1024 sc1
	s_add_u32 s16, s16, 0xdd400
	s_addc_u32 s17, s17, 0
	s_waitcnt vmcnt(0)
	v_cmp_eq_u32_e32 vcc, v0, v116
	s_and_saveexec_b64 s[18:19], vcc
	s_cbranch_execz .LBB0_1499
	s_mov_b64 s[20:21], 0
.LBB0_1498:
	s_sleep 0
	global_load_dword v0, v179, s[16:17] sc1
	s_waitcnt vmcnt(0)
	v_cmp_ne_u32_e32 vcc, v0, v116
	s_or_b64 s[20:21], vcc, s[20:21]
	s_andn2_b64 exec, exec, s[20:21]
	s_cbranch_execnz .LBB0_1498
.LBB0_1499:
	s_or_b64 exec, exec, s[18:19]
	s_waitcnt vmcnt(0)
.LBB0_1500:
	s_andn2_saveexec_b64 s[14:15], s[14:15]
	s_cbranch_execz .LBB0_1515
	s_mov_b64 s[16:17], exec
	buffer_wbl2 sc1
	s_waitcnt vmcnt(0)
	v_mbcnt_lo_u32_b32 v1, s16, 0
	v_mbcnt_hi_u32_b32 v1, s17, v1
	v_cmp_eq_u32_e32 vcc, 0, v1
	s_and_saveexec_b64 s[18:19], vcc
	s_cbranch_execz .LBB0_1503
	s_bcnt1_i32_b64 s16, s[16:17]
	v_mov_b32_e32 v2, s16
	v_mov_b32_e32 v3, 0xde000
	global_atomic_add v2, v3, v2, s[12:13] offset:1024 sc0
.LBB0_1503:
	s_or_b64 exec, exec, s[18:19]
	s_waitcnt vmcnt(0)
	buffer_inv sc1
	v_readfirstlane_b32 s16, v2
	v_mul_lo_u32 v0, v0, v97
	s_nop 0
	v_add3_u32 v1, s16, v1, 1
	s_add_u32 s16, s12, 0xde500
	v_cmp_ne_u32_e32 vcc, v1, v0
	s_addc_u32 s17, s13, 0
	s_and_saveexec_b64 s[18:19], vcc
	s_xor_b64 s[18:19], exec, s[18:19]
	s_cbranch_execz .LBB0_1508
	global_load_dword v0, v179, s[16:17] sc1
	s_waitcnt vmcnt(0)
	v_cmp_eq_u32_e32 vcc, v0, v116
	s_and_saveexec_b64 s[20:21], vcc
	s_cbranch_execz .LBB0_1507
	s_mov_b64 s[22:23], 0

.LBB0_1599:
	s_or_b64 exec, exec, s[16:17]
	s_waitcnt vmcnt(0)
	v_readfirstlane_b32 s14, v3
	s_waitcnt lgkmcnt(0)
	v_mul_lo_u32 v1, v1, v24
	v_add3_u32 v2, s14, v2, 1
	v_cmp_ne_u32_e32 vcc, v2, v1
	s_and_saveexec_b64 s[14:15], vcc
	s_xor_b64 s[14:15], exec, s[14:15]
	s_cbranch_execz .LBB0_1604
	s_lshl_b64 s[16:17], s[40:41], 2
	s_add_u32 s16, s12, s16
	s_addc_u32 s17, s13, s17
	v_mov_b32_e32 v0, 0xdd000
	buffer_inv sc1
	global_load_dword v0, v0, s[16:17] offset:1024 sc1
	s_add_u32 s16, s16, 0xdd400
	s_addc_u32 s17, s17, 0
	s_waitcnt vmcnt(0)
	v_cmp_eq_u32_e32 vcc, v0, v97
	s_and_saveexec_b64 s[18:19], vcc
	s_cbranch_execz .LBB0_1603
	s_mov_b64 s[20:21], 0
.LBB0_1602:
	s_sleep 0
	global_load_dword v0, v179, s[16:17] sc1
	s_waitcnt vmcnt(0)
	v_cmp_ne_u32_e32 vcc, v0, v97
	s_or_b64 s[20:21], vcc, s[20:21]
	s_andn2_b64 exec, exec, s[20:21]
	s_cbranch_execnz .LBB0_1602
.LBB0_1603:
	s_or_b64 exec, exec, s[18:19]
	s_waitcnt vmcnt(0)
.LBB0_1604:
	s_andn2_saveexec_b64 s[14:15], s[14:15]
	s_cbranch_execz .LBB0_1619
	s_mov_b64 s[16:17], exec
	buffer_wbl2 sc1
	s_waitcnt vmcnt(0)
	v_mbcnt_lo_u32_b32 v1, s16, 0
	v_mbcnt_hi_u32_b32 v1, s17, v1
	v_cmp_eq_u32_e32 vcc, 0, v1
	s_and_saveexec_b64 s[18:19], vcc
	s_cbranch_execz .LBB0_1607
	s_bcnt1_i32_b64 s16, s[16:17]
	v_mov_b32_e32 v2, s16
	v_mov_b32_e32 v3, 0xde000
	global_atomic_add v2, v3, v2, s[12:13] offset:1024 sc0
.LBB0_1607:
	s_or_b64 exec, exec, s[18:19]
	s_waitcnt vmcnt(0)
	buffer_inv sc1
	v_readfirstlane_b32 s16, v2
	v_mul_lo_u32 v0, v0, v24
	s_nop 0
	v_add3_u32 v1, s16, v1, 1
	s_add_u32 s16, s12, 0xde500
	v_cmp_ne_u32_e32 vcc, v1, v0
	s_addc_u32 s17, s13, 0
	s_and_saveexec_b64 s[18:19], vcc
	s_xor_b64 s[18:19], exec, s[18:19]
	s_cbranch_execz .LBB0_1612
	global_load_dword v0, v179, s[16:17] sc1
	s_waitcnt vmcnt(0)
	v_cmp_eq_u32_e32 vcc, v0, v97
	s_and_saveexec_b64 s[20:21], vcc
	s_cbranch_execz .LBB0_1611
	s_mov_b64 s[22:23], 0

.LBB0_1675:
	s_or_b64 exec, exec, s[16:17]
	s_waitcnt vmcnt(0)
	v_readfirstlane_b32 s14, v3
	s_waitcnt lgkmcnt(0)
	v_mul_lo_u32 v1, v1, v97
	v_add3_u32 v2, s14, v2, 1
	v_cmp_ne_u32_e32 vcc, v2, v1
	s_and_saveexec_b64 s[14:15], vcc
	s_xor_b64 s[14:15], exec, s[14:15]
	s_cbranch_execz .LBB0_1680
	s_lshl_b64 s[16:17], s[40:41], 2
	s_add_u32 s16, s12, s16
	s_addc_u32 s17, s13, s17
	v_mov_b32_e32 v0, 0xdd000
	buffer_inv sc1
	global_load_dword v0, v0, s[16:17] offset:1024 sc1
	s_add_u32 s16, s16, 0xdd400
	s_addc_u32 s17, s17, 0
	s_waitcnt vmcnt(0)
	v_cmp_eq_u32_e32 vcc, v0, v24
	s_and_saveexec_b64 s[18:19], vcc
	s_cbranch_execz .LBB0_1679
	s_mov_b64 s[20:21], 0
.LBB0_1678:
	s_sleep 0
	global_load_dword v0, v179, s[16:17] sc1
	s_waitcnt vmcnt(0)
	v_cmp_ne_u32_e32 vcc, v0, v24
	s_or_b64 s[20:21], vcc, s[20:21]
	s_andn2_b64 exec, exec, s[20:21]
	s_cbranch_execnz .LBB0_1678
.LBB0_1679:
	s_or_b64 exec, exec, s[18:19]
	s_waitcnt vmcnt(0)
.LBB0_1680:
	s_andn2_saveexec_b64 s[14:15], s[14:15]
	s_cbranch_execz .LBB0_1695
	s_mov_b64 s[16:17], exec
	buffer_wbl2 sc1
	s_waitcnt vmcnt(0)
	v_mbcnt_lo_u32_b32 v1, s16, 0
	v_mbcnt_hi_u32_b32 v1, s17, v1
	v_cmp_eq_u32_e32 vcc, 0, v1
	s_and_saveexec_b64 s[18:19], vcc
	s_cbranch_execz .LBB0_1683
	s_bcnt1_i32_b64 s16, s[16:17]
	v_mov_b32_e32 v2, s16
	v_mov_b32_e32 v3, 0xde000
	global_atomic_add v2, v3, v2, s[12:13] offset:1024 sc0
.LBB0_1683:
	s_or_b64 exec, exec, s[18:19]
	s_waitcnt vmcnt(0)
	buffer_inv sc1
	v_readfirstlane_b32 s16, v2
	v_mul_lo_u32 v0, v0, v97
	s_nop 0
	v_add3_u32 v1, s16, v1, 1
	s_add_u32 s16, s12, 0xde500
	v_cmp_ne_u32_e32 vcc, v1, v0
	s_addc_u32 s17, s13, 0
	s_and_saveexec_b64 s[18:19], vcc
	s_xor_b64 s[18:19], exec, s[18:19]
	s_cbranch_execz .LBB0_1688
	global_load_dword v0, v179, s[16:17] sc1
	s_waitcnt vmcnt(0)
	v_cmp_eq_u32_e32 vcc, v0, v24
	s_and_saveexec_b64 s[20:21], vcc
	s_cbranch_execz .LBB0_1687
	s_mov_b64 s[22:23], 0

.LBB0_1777:
	s_or_b64 exec, exec, s[16:17]
	s_waitcnt vmcnt(0)
	v_readfirstlane_b32 s14, v3
	s_waitcnt lgkmcnt(0)
	v_mul_lo_u32 v1, v1, v149
	v_add3_u32 v2, s14, v2, 1
	v_cmp_ne_u32_e32 vcc, v2, v1
	s_and_saveexec_b64 s[14:15], vcc
	s_xor_b64 s[14:15], exec, s[14:15]
	s_cbranch_execz .LBB0_1782
	s_lshl_b64 s[16:17], s[40:41], 2
	s_add_u32 s16, s12, s16
	s_addc_u32 s17, s13, s17
	v_mov_b32_e32 v0, 0xdd000
	buffer_inv sc1
	global_load_dword v0, v0, s[16:17] offset:1024 sc1
	s_add_u32 s16, s16, 0xdd400
	s_addc_u32 s17, s17, 0
	s_waitcnt vmcnt(0)
	v_cmp_eq_u32_e32 vcc, v0, v97
	s_and_saveexec_b64 s[18:19], vcc
	s_cbranch_execz .LBB0_1781
	s_mov_b64 s[20:21], 0
.LBB0_1780:
	s_sleep 0
	global_load_dword v0, v179, s[16:17] sc1
	s_waitcnt vmcnt(0)
	v_cmp_ne_u32_e32 vcc, v0, v97
	s_or_b64 s[20:21], vcc, s[20:21]
	s_andn2_b64 exec, exec, s[20:21]
	s_cbranch_execnz .LBB0_1780
.LBB0_1781:
	s_or_b64 exec, exec, s[18:19]
	s_waitcnt vmcnt(0)
.LBB0_1782:
	s_andn2_saveexec_b64 s[14:15], s[14:15]
	s_cbranch_execz .LBB0_1797
	s_mov_b64 s[16:17], exec
	buffer_wbl2 sc1
	s_waitcnt vmcnt(0)
	v_mbcnt_lo_u32_b32 v1, s16, 0
	v_mbcnt_hi_u32_b32 v1, s17, v1
	v_cmp_eq_u32_e32 vcc, 0, v1
	s_and_saveexec_b64 s[18:19], vcc
	s_cbranch_execz .LBB0_1785
	s_bcnt1_i32_b64 s16, s[16:17]
	v_mov_b32_e32 v2, s16
	v_mov_b32_e32 v3, 0xde000
	global_atomic_add v2, v3, v2, s[12:13] offset:1024 sc0
.LBB0_1785:
	s_or_b64 exec, exec, s[18:19]
	s_waitcnt vmcnt(0)
	buffer_inv sc1
	v_readfirstlane_b32 s16, v2
	v_mul_lo_u32 v0, v0, v149
	s_nop 0
	v_add3_u32 v1, s16, v1, 1
	s_add_u32 s16, s12, 0xde500
	v_cmp_ne_u32_e32 vcc, v1, v0
	s_addc_u32 s17, s13, 0
	s_and_saveexec_b64 s[18:19], vcc
	s_xor_b64 s[18:19], exec, s[18:19]
	s_cbranch_execz .LBB0_1790
	global_load_dword v0, v179, s[16:17] sc1
	s_waitcnt vmcnt(0)
	v_cmp_eq_u32_e32 vcc, v0, v97
	s_and_saveexec_b64 s[20:21], vcc
	s_cbranch_execz .LBB0_1789
	s_mov_b64 s[22:23], 0

.LBB0_1854:
	s_or_b64 exec, exec, s[16:17]
	s_waitcnt vmcnt(0)
	v_readfirstlane_b32 s14, v3
	s_waitcnt lgkmcnt(0)
	v_mul_lo_u32 v1, v1, v97
	v_add3_u32 v2, s14, v2, 1
	v_cmp_ne_u32_e32 vcc, v2, v1
	s_and_saveexec_b64 s[14:15], vcc
	s_xor_b64 s[14:15], exec, s[14:15]
	s_cbranch_execz .LBB0_1859
	s_lshl_b64 s[16:17], s[40:41], 2
	s_add_u32 s16, s12, s16
	s_addc_u32 s17, s13, s17
	v_mov_b32_e32 v0, 0xdd000
	buffer_inv sc1
	global_load_dword v0, v0, s[16:17] offset:1024 sc1
	s_add_u32 s16, s16, 0xdd400
	s_addc_u32 s17, s17, 0
	s_waitcnt vmcnt(0)
	v_cmp_eq_u32_e32 vcc, v0, v149
	s_and_saveexec_b64 s[18:19], vcc
	s_cbranch_execz .LBB0_1858
	s_mov_b64 s[20:21], 0
.LBB0_1857:
	s_sleep 0
	global_load_dword v0, v179, s[16:17] sc1
	s_waitcnt vmcnt(0)
	v_cmp_ne_u32_e32 vcc, v0, v149
	s_or_b64 s[20:21], vcc, s[20:21]
	s_andn2_b64 exec, exec, s[20:21]
	s_cbranch_execnz .LBB0_1857
.LBB0_1858:
	s_or_b64 exec, exec, s[18:19]
	s_waitcnt vmcnt(0)
.LBB0_1859:
	s_andn2_saveexec_b64 s[14:15], s[14:15]
	s_cbranch_execz .LBB0_1874
	s_mov_b64 s[16:17], exec
	buffer_wbl2 sc1
	s_waitcnt vmcnt(0)
	v_mbcnt_lo_u32_b32 v1, s16, 0
	v_mbcnt_hi_u32_b32 v1, s17, v1
	v_cmp_eq_u32_e32 vcc, 0, v1
	s_and_saveexec_b64 s[18:19], vcc
	s_cbranch_execz .LBB0_1862
	s_bcnt1_i32_b64 s16, s[16:17]
	v_mov_b32_e32 v2, s16
	v_mov_b32_e32 v3, 0xde000
	global_atomic_add v2, v3, v2, s[12:13] offset:1024 sc0
.LBB0_1862:
	s_or_b64 exec, exec, s[18:19]
	s_waitcnt vmcnt(0)
	buffer_inv sc1
	v_readfirstlane_b32 s16, v2
	v_mul_lo_u32 v0, v0, v97
	s_nop 0
	v_add3_u32 v1, s16, v1, 1
	s_add_u32 s16, s12, 0xde500
	v_cmp_ne_u32_e32 vcc, v1, v0
	s_addc_u32 s17, s13, 0
	s_and_saveexec_b64 s[18:19], vcc
	s_xor_b64 s[18:19], exec, s[18:19]
	s_cbranch_execz .LBB0_1867
	global_load_dword v0, v179, s[16:17] sc1
	s_waitcnt vmcnt(0)
	v_cmp_eq_u32_e32 vcc, v0, v149
	s_and_saveexec_b64 s[20:21], vcc
	s_cbranch_execz .LBB0_1866
	s_mov_b64 s[22:23], 0

.LBB0_1901:
	s_or_b64 exec, exec, s[16:17]
	s_waitcnt vmcnt(0)
	v_readfirstlane_b32 s14, v3
	s_waitcnt lgkmcnt(0)
	v_mul_lo_u32 v1, v1, v142
	v_add3_u32 v2, s14, v2, 1
	v_cmp_ne_u32_e32 vcc, v2, v1
	s_and_saveexec_b64 s[14:15], vcc
	s_xor_b64 s[14:15], exec, s[14:15]
	s_cbranch_execz .LBB0_1906
	s_lshl_b64 s[16:17], s[40:41], 2
	s_add_u32 s16, s12, s16
	s_addc_u32 s17, s13, s17
	v_mov_b32_e32 v0, 0xdd000
	buffer_inv sc1
	global_load_dword v0, v0, s[16:17] offset:1024 sc1
	s_add_u32 s16, s16, 0xdd400
	s_addc_u32 s17, s17, 0
	s_waitcnt vmcnt(0)
	v_cmp_eq_u32_e32 vcc, v0, v97
	s_and_saveexec_b64 s[18:19], vcc
	s_cbranch_execz .LBB0_1905
	s_mov_b64 s[20:21], 0
.LBB0_1904:
	s_sleep 0
	global_load_dword v0, v179, s[16:17] sc1
	s_waitcnt vmcnt(0)
	v_cmp_ne_u32_e32 vcc, v0, v97
	s_or_b64 s[20:21], vcc, s[20:21]
	s_andn2_b64 exec, exec, s[20:21]
	s_cbranch_execnz .LBB0_1904
.LBB0_1905:
	s_or_b64 exec, exec, s[18:19]
	s_waitcnt vmcnt(0)
.LBB0_1906:
	s_andn2_saveexec_b64 s[14:15], s[14:15]
	s_cbranch_execz .LBB0_1921
	s_mov_b64 s[16:17], exec
	buffer_wbl2 sc1
	s_waitcnt vmcnt(0)
	v_mbcnt_lo_u32_b32 v1, s16, 0
	v_mbcnt_hi_u32_b32 v1, s17, v1
	v_cmp_eq_u32_e32 vcc, 0, v1
	s_and_saveexec_b64 s[18:19], vcc
	s_cbranch_execz .LBB0_1909
	s_bcnt1_i32_b64 s16, s[16:17]
	v_mov_b32_e32 v2, s16
	v_mov_b32_e32 v3, 0xde000
	global_atomic_add v2, v3, v2, s[12:13] offset:1024 sc0
.LBB0_1909:
	s_or_b64 exec, exec, s[18:19]
	s_waitcnt vmcnt(0)
	buffer_inv sc1
	v_readfirstlane_b32 s16, v2
	v_mul_lo_u32 v0, v0, v142
	s_nop 0
	v_add3_u32 v1, s16, v1, 1
	s_add_u32 s16, s12, 0xde500
	v_cmp_ne_u32_e32 vcc, v1, v0
	s_addc_u32 s17, s13, 0
	s_and_saveexec_b64 s[18:19], vcc
	s_xor_b64 s[18:19], exec, s[18:19]
	s_cbranch_execz .LBB0_1914
	global_load_dword v0, v179, s[16:17] sc1
	s_waitcnt vmcnt(0)
	v_cmp_eq_u32_e32 vcc, v0, v97
	s_and_saveexec_b64 s[20:21], vcc
	s_cbranch_execz .LBB0_1913
	s_mov_b64 s[22:23], 0

.LBB0_1965:
	s_or_b64 exec, exec, s[16:17]
	s_waitcnt vmcnt(0)
	v_readfirstlane_b32 s14, v3
	s_waitcnt lgkmcnt(0)
	v_mul_lo_u32 v1, v1, v97
	v_add3_u32 v2, s14, v2, 1
	v_cmp_ne_u32_e32 vcc, v2, v1
	s_and_saveexec_b64 s[14:15], vcc
	s_xor_b64 s[14:15], exec, s[14:15]
	s_cbranch_execz .LBB0_1970
	s_lshl_b64 s[16:17], s[40:41], 2
	s_add_u32 s16, s12, s16
	s_addc_u32 s17, s13, s17
	v_mov_b32_e32 v0, 0xdd000
	buffer_inv sc1
	global_load_dword v0, v0, s[16:17] offset:1024 sc1
	s_add_u32 s16, s16, 0xdd400
	s_addc_u32 s17, s17, 0
	s_waitcnt vmcnt(0)
	v_cmp_eq_u32_e32 vcc, v0, v142
	s_and_saveexec_b64 s[18:19], vcc
	s_cbranch_execz .LBB0_1969
	s_mov_b64 s[20:21], 0
.LBB0_1968:
	s_sleep 0
	global_load_dword v0, v179, s[16:17] sc1
	s_waitcnt vmcnt(0)
	v_cmp_ne_u32_e32 vcc, v0, v142
	s_or_b64 s[20:21], vcc, s[20:21]
	s_andn2_b64 exec, exec, s[20:21]
	s_cbranch_execnz .LBB0_1968
.LBB0_1969:
	s_or_b64 exec, exec, s[18:19]
	s_waitcnt vmcnt(0)
.LBB0_1970:
	s_andn2_saveexec_b64 s[14:15], s[14:15]
	s_cbranch_execz .LBB0_1985
	s_mov_b64 s[16:17], exec
	buffer_wbl2 sc1
	s_waitcnt vmcnt(0)
	v_mbcnt_lo_u32_b32 v1, s16, 0
	v_mbcnt_hi_u32_b32 v1, s17, v1
	v_cmp_eq_u32_e32 vcc, 0, v1
	s_and_saveexec_b64 s[18:19], vcc
	s_cbranch_execz .LBB0_1973
	s_bcnt1_i32_b64 s16, s[16:17]
	v_mov_b32_e32 v2, s16
	v_mov_b32_e32 v3, 0xde000
	global_atomic_add v2, v3, v2, s[12:13] offset:1024 sc0
.LBB0_1973:
	s_or_b64 exec, exec, s[18:19]
	s_waitcnt vmcnt(0)
	buffer_inv sc1
	v_readfirstlane_b32 s16, v2
	v_mul_lo_u32 v0, v0, v97
	s_nop 0
	v_add3_u32 v1, s16, v1, 1
	s_add_u32 s16, s12, 0xde500
	v_cmp_ne_u32_e32 vcc, v1, v0
	s_addc_u32 s17, s13, 0
	s_and_saveexec_b64 s[18:19], vcc
	s_xor_b64 s[18:19], exec, s[18:19]
	s_cbranch_execz .LBB0_1978
	global_load_dword v0, v179, s[16:17] sc1
	s_waitcnt vmcnt(0)
	v_cmp_eq_u32_e32 vcc, v0, v142
	s_and_saveexec_b64 s[20:21], vcc
	s_cbranch_execz .LBB0_1977
	s_mov_b64 s[22:23], 0

.LBB0_2039:
	s_or_b64 exec, exec, s[14:15]
	s_waitcnt vmcnt(0)
	v_readfirstlane_b32 s12, v4
	s_waitcnt lgkmcnt(0)
	v_mul_lo_u32 v2, v2, v0
	v_add3_u32 v3, s12, v3, 1
	v_cmp_ne_u32_e32 vcc, v3, v2
	s_and_saveexec_b64 s[12:13], vcc
	s_xor_b64 s[12:13], exec, s[12:13]
	s_cbranch_execz .LBB0_2044
	s_lshl_b64 s[14:15], s[40:41], 2
	s_add_u32 s14, s10, s14
	s_addc_u32 s15, s11, s15
	v_mov_b32_e32 v1, 0xdd000
	buffer_inv sc1
	global_load_dword v1, v1, s[14:15] offset:1024 sc1
	s_add_u32 s14, s14, 0xdd400
	s_addc_u32 s15, s15, 0
	s_waitcnt vmcnt(0)
	v_cmp_eq_u32_e32 vcc, v1, v97
	s_and_saveexec_b64 s[16:17], vcc
	s_cbranch_execz .LBB0_2043
	s_mov_b64 s[18:19], 0
.LBB0_2042:
	s_sleep 0
	global_load_dword v1, v179, s[14:15] sc1
	s_waitcnt vmcnt(0)
	v_cmp_ne_u32_e32 vcc, v1, v97
	s_or_b64 s[18:19], vcc, s[18:19]
	s_andn2_b64 exec, exec, s[18:19]
	s_cbranch_execnz .LBB0_2042
.LBB0_2043:
	s_or_b64 exec, exec, s[16:17]
	s_waitcnt vmcnt(0)
.LBB0_2044:
	s_andn2_saveexec_b64 s[12:13], s[12:13]
	s_cbranch_execz .LBB0_2059
	s_mov_b64 s[14:15], exec
	buffer_wbl2 sc1
	s_waitcnt vmcnt(0)
	v_mbcnt_lo_u32_b32 v2, s14, 0
	v_mbcnt_hi_u32_b32 v2, s15, v2
	v_cmp_eq_u32_e32 vcc, 0, v2
	s_and_saveexec_b64 s[16:17], vcc
	s_cbranch_execz .LBB0_2047
	s_bcnt1_i32_b64 s14, s[14:15]
	v_mov_b32_e32 v3, s14
	v_mov_b32_e32 v4, 0xde000
	global_atomic_add v3, v4, v3, s[10:11] offset:1024 sc0
.LBB0_2047:
	s_or_b64 exec, exec, s[16:17]
	s_waitcnt vmcnt(0)
	buffer_inv sc1
	v_readfirstlane_b32 s14, v3
	v_mul_lo_u32 v1, v1, v0
	s_nop 0
	v_add3_u32 v2, s14, v2, 1
	s_add_u32 s14, s10, 0xde500
	v_cmp_ne_u32_e32 vcc, v2, v1
	s_addc_u32 s15, s11, 0
	s_and_saveexec_b64 s[16:17], vcc
	s_xor_b64 s[16:17], exec, s[16:17]
	s_cbranch_execz .LBB0_2052
	global_load_dword v1, v179, s[14:15] sc1
	s_waitcnt vmcnt(0)
	v_cmp_eq_u32_e32 vcc, v1, v97
	s_and_saveexec_b64 s[18:19], vcc
	s_cbranch_execz .LBB0_2051
	s_mov_b64 s[20:21], 0

.LBB0_2056:
	s_or_b64 exec, exec, s[16:17]
	s_mov_b64 s[14:15], exec
	v_mbcnt_lo_u32_b32 v1, s14, 0
	v_mbcnt_hi_u32_b32 v1, s15, v1
	v_cmp_eq_u32_e32 vcc, 0, v1
	s_waitcnt vmcnt(0)
	s_and_saveexec_b64 s[16:17], vcc
	s_cbranch_execz .LBB0_2058
	s_lshl_b64 s[18:19], s[40:41], 2
	s_add_u32 s10, s10, s18
	s_addc_u32 s11, s11, s19
	s_bcnt1_i32_b64 s14, s[14:15]
	v_mov_b32_e32 v1, s14
	v_mov_b32_e32 v2, 0xdd000
	global_atomic_add v2, v1, s[10:11] offset:1024
